# static s_setprio 1 for waves 0-3 through the attention phases (other half than the earlier test)
# speedup vs baseline: 1.0044x; 1.0044x over previous
; DI float shx(float v, int m, int lane) { return __int_as_float(__builtin_amdgcn_ds_bpermute((lane ^ m) << 2, __float_as_int(v))); }
; DI float uni(float v) { return __int_as_float(__builtin_amdgcn_readfirstlane(__float_as_int(v))); }
; DI float wave_absmax(const float* w, int n, int lane) {
;     float m = 0.f;
;     for (int i = lane; i < n; i += 64) m = fmaxf(m, fabsf(w[i]));
; #pragma unroll
;     for (int o = 1; o < 64; o <<= 1) m = fmaxf(m, shx(m, o, lane));
;     return m;
; __global__ void __launch_bounds__(512) mega(Params P) {
;     ...
;             const float nbound = uni(-(64.0f * 0.125f * LOG2E * 1.02f) * wave_absmax(P.gqa_qk_norm + (l * 2 + 0) * 64, 64, lane) * wave_absmax(P.gqa_qk_norm + (l * 2 + 1) * 64, 64, lane));
;             for (int u = vcu; u < 256; u += G) {
.LBB0_380:
	s_or_b64 exec, exec, s[2:3]
	ds_bpermute_b32 v1, v7, v4
	v_max_f32_e32 v2, v4, v4
	s_waitcnt lgkmcnt(1)
	v_max_f32_e32 v3, v14, v14
	v_max_f32_e32 v4, v12, v12
	v_max_f32_e32 v3, v4, v3
	s_waitcnt lgkmcnt(0)
	v_max_f32_e32 v1, v1, v1
	v_max_f32_e32 v1, v2, v1
	ds_bpermute_b32 v2, v8, v1
	v_mul_f32_e32 v3, 0xc13c5bb7, v3
	s_cmpk_gt_i32 s20, 0xff
	s_waitcnt lgkmcnt(0)
	v_max_f32_e32 v2, v2, v2
	v_max_f32_e32 v1, v1, v2
	ds_bpermute_b32 v2, v9, v1
	s_waitcnt lgkmcnt(0)
	v_max_f32_e32 v2, v2, v2
	v_max_f32_e32 v1, v1, v2
	ds_bpermute_b32 v2, v10, v1
	s_waitcnt lgkmcnt(0)
	v_max_f32_e32 v2, v2, v2
	v_max_f32_e32 v1, v1, v2
	ds_bpermute_b32 v2, v11, v1
	s_waitcnt lgkmcnt(0)
	v_max_f32_e32 v2, v2, v2
	v_max_f32_e32 v1, v1, v2
	ds_bpermute_b32 v2, v13, v1
	s_waitcnt lgkmcnt(0)
	v_max_f32_e32 v2, v2, v2
	v_max_f32_e32 v1, v1, v2
	v_mul_f32_e32 v1, v3, v1
	s_nop 0
	v_readfirstlane_b32 s48, v1
	s_cbranch_scc1 .LBB0_385
	s_cmp_ge_u32 s14, 4
	s_cbranch_scc1 .Lprio_attn_skip
	s_setprio 1
